# speedup vs baseline: 1.0031x; 1.0031x over previous
; DI void attn_s(const unsigned char* sK, int tt, int qb, int qs, int sub, int l31, int h,
;                const bf16x8 (&qf)[4], f32x16 (&O)[4], float& m, float& l, bf16x8 (&pb)[4]) {
;     ...
;     } else if (tt >= 2 * qb + 1) {
;         const int kbase = (tt - 1) * 64 + 4 * h;
; #pragma unroll
;         for (int k2 = 0; k2 < 2; ++k2)
; #pragma unroll
;             for (int i = 0; i < 16; ++i) {
;                 const int key = kbase + k2 * 32 + (i & 3) + 8 * (i >> 2);
;                 if (key > qs) st[k2][i] = -INFINITY;
;             }
;     }
; DI void attn_pv(const unsigned char* sV, int l31, int h, const bf16x8 (&pb)[4], f32x16 (&O)[4]) {
;     ...
;         const unsigned char* vb = sV + l31 * A_VROWB + 16 * h;
;         bf16x8 va[4], vc[4];
; #pragma unroll
;         for (int d = 0; d < 4; ++d) va[d] = *(const bf16x8*)(vb + d * 32 * A_VROWB);
;         __builtin_amdgcn_sched_barrier(0);
; #pragma unroll
;         for (int d = 0; d < 4; ++d) vc[d] = *(const bf16x8*)(vb + d * 32 * A_VROWB + 32);
.Lpipe_loop:
	s_barrier
	v_add3_u32 v191, s98, v156, v98
	ds_read_b128 v[172:175], v191 offset:17408
	ds_read_b128 v[176:179], v191 offset:22016
	ds_read_b128 v[180:183], v191 offset:26624
	ds_read_b128 v[192:195], v191 offset:31232
	ds_read_b128 v[200:203], v191 offset:17440
	ds_read_b128 v[204:207], v191 offset:22048
	ds_read_b128 v[208:211], v191 offset:26656
	ds_read_b128 v[212:215], v191 offset:31264
	s_add_i32 s14, s12, 0x41
	s_cmp_le_i32 s14, s0
	s_cbranch_scc1 .Lpipe_nomask_l
	v_subrev_u32_e32 v159, 59, v158
	v_cmp_gt_i32_e32 vcc, v159, v138
	s_nop 1
	v_cndmask_b32_e32 v160, v82, v188, vcc
	v_cmp_lt_i32_e32 vcc, v159, v138
	v_subrev_u32_e32 v159, 57, v158
	s_nop 0
	v_cndmask_b32_e32 v82, v160, v82, vcc
	v_cndmask_b32_e32 v83, v188, v83, vcc
	v_cmp_le_i32_e32 vcc, v159, v138
	v_subrev_u32_e32 v159, 56, v158
	s_nop 0
	v_cndmask_b32_e32 v84, v188, v84, vcc
	v_cmp_le_i32_e32 vcc, v159, v138
	v_subrev_u32_e32 v159, 51, v158
	s_nop 0
	v_cndmask_b32_e32 v85, v188, v85, vcc
	v_cmp_le_i32_e32 vcc, v159, v138
	v_subrev_u32_e32 v159, 50, v158
	s_nop 0
	v_cndmask_b32_e32 v86, v188, v86, vcc
	v_cmp_le_i32_e32 vcc, v159, v138
	v_subrev_u32_e32 v159, 49, v158
	s_nop 0
	v_cndmask_b32_e32 v87, v188, v87, vcc
	v_cmp_le_i32_e32 vcc, v159, v138
	v_subrev_u32_e32 v159, 48, v158
	s_nop 0
	v_cndmask_b32_e32 v88, v188, v88, vcc
	v_cmp_le_i32_e32 vcc, v159, v138
	v_subrev_u32_e32 v159, 43, v158
	s_nop 0
	v_cndmask_b32_e32 v89, v188, v89, vcc
	v_cmp_le_i32_e32 vcc, v159, v138
	v_subrev_u32_e32 v159, 42, v158
	s_nop 0
	v_cndmask_b32_e32 v90, v188, v90, vcc
	v_cmp_le_i32_e32 vcc, v159, v138
	v_subrev_u32_e32 v159, 41, v158
	s_nop 0
	v_cndmask_b32_e32 v91, v188, v91, vcc
	v_cmp_le_i32_e32 vcc, v159, v138
	v_subrev_u32_e32 v159, 40, v158
	s_nop 0
	v_cndmask_b32_e32 v92, v188, v92, vcc
	v_cmp_le_i32_e32 vcc, v159, v138
	v_subrev_u32_e32 v159, 35, v158
	s_nop 0
	v_cndmask_b32_e32 v93, v188, v93, vcc
	v_cmp_le_i32_e32 vcc, v159, v138
	v_subrev_u32_e32 v159, 34, v158
	s_nop 0
	v_cndmask_b32_e32 v94, v188, v94, vcc
	v_cmp_le_i32_e32 vcc, v159, v138
	v_subrev_u32_e32 v159, 33, v158
	s_nop 0
	v_cndmask_b32_e32 v95, v188, v95, vcc
	v_cmp_le_i32_e32 vcc, v159, v138
	v_subrev_u32_e32 v159, 32, v158
	s_nop 0
	v_cndmask_b32_e32 v96, v188, v96, vcc
	v_cmp_le_i32_e32 vcc, v159, v138
	v_subrev_u32_e32 v159, 27, v158
	s_nop 0
	v_cndmask_b32_e32 v97, v188, v97, vcc
	v_cmp_le_i32_e32 vcc, v159, v138
	v_subrev_u32_e32 v159, 26, v158
	s_nop 0
	v_cndmask_b32_e32 v66, v188, v66, vcc
	v_cmp_le_i32_e32 vcc, v159, v138
	v_subrev_u32_e32 v159, 25, v158
	s_nop 0
	v_cndmask_b32_e32 v67, v188, v67, vcc
	v_cmp_le_i32_e32 vcc, v159, v138
	v_subrev_u32_e32 v159, 24, v158
	s_nop 0
	v_cndmask_b32_e32 v68, v188, v68, vcc
	v_cmp_le_i32_e32 vcc, v159, v138
	v_subrev_u32_e32 v159, 19, v158
	s_nop 0
	v_cndmask_b32_e32 v69, v188, v69, vcc
	v_cmp_le_i32_e32 vcc, v159, v138
	v_subrev_u32_e32 v159, 18, v158
	s_nop 0
	v_cndmask_b32_e32 v70, v188, v70, vcc
	v_cmp_le_i32_e32 vcc, v159, v138
	v_subrev_u32_e32 v159, 17, v158
	s_nop 0
	v_cndmask_b32_e32 v71, v188, v71, vcc
	v_cmp_le_i32_e32 vcc, v159, v138
	v_add_u32_e32 v159, -16, v158
	s_nop 0
	v_cndmask_b32_e32 v72, v188, v72, vcc
	v_cmp_le_i32_e32 vcc, v159, v138
	v_add_u32_e32 v159, -11, v158
	s_nop 0
	v_cndmask_b32_e32 v73, v188, v73, vcc
	v_cmp_le_i32_e32 vcc, v159, v138
	v_add_u32_e32 v159, -10, v158
	s_nop 0
	v_cndmask_b32_e32 v74, v188, v74, vcc
	v_cmp_le_i32_e32 vcc, v159, v138
	v_add_u32_e32 v159, -9, v158
	s_nop 0
	v_cndmask_b32_e32 v75, v188, v75, vcc
	v_cmp_le_i32_e32 vcc, v159, v138
	v_add_u32_e32 v159, -8, v158
	s_nop 0
	v_cndmask_b32_e32 v76, v188, v76, vcc
	v_cmp_le_i32_e32 vcc, v159, v138
	v_add_u32_e32 v159, -3, v158
	s_nop 0
	v_cndmask_b32_e32 v77, v188, v77, vcc
	v_cmp_le_i32_e32 vcc, v159, v138
	v_add_u32_e32 v159, -2, v158
	s_nop 0
	v_cndmask_b32_e32 v78, v188, v78, vcc
	v_cmp_le_i32_e32 vcc, v159, v138
	v_add_u32_e32 v159, -1, v158
	s_nop 0
	v_cndmask_b32_e32 v79, v188, v79, vcc
	v_cmp_le_i32_e32 vcc, v159, v138
	s_nop 1
	v_cndmask_b32_e32 v80, v188, v80, vcc
	v_cmp_le_i32_e32 vcc, v158, v138
	s_nop 1
	v_cndmask_b32_e32 v81, v188, v81, vcc

; #define MFMA32(a, b, c) __builtin_amdgcn_mfma_f32_32x32x16_bf16((a), (b), (c), 0, 0, 0)
; DI void attn_pv(const unsigned char* sV, int l31, int h, const bf16x8 (&pb)[4], f32x16 (&O)[4]) {
;     ...
; #pragma unroll
;         for (int d = 0; d < 4; ++d) O[d] = MFMA32(vc[d], pb[3], O[d]);
; DI void attn_item(const Params& p, unsigned char* lds, int b, int hd, int qb, float lam) {
;     ...
;         __syncthreads();
;         bp = bc; bc = bn; bn = (bn == 2) ? 0 : bn + 1;
.Lpipe_k3:
	s_waitcnt lgkmcnt(4)
	v_mfma_f32_32x32x16_bf16 v[50:65], v[160:163], v[228:231], v[50:65]
	v_mfma_f32_32x32x16_bf16 v[34:49], v[164:167], v[228:231], v[34:49]
	v_mfma_f32_32x32x16_bf16 v[18:33], v[168:171], v[228:231], v[18:33]
	v_mfma_f32_32x32x16_bf16 v[2:17], v[196:199], v[228:231], v[2:17]
	s_setprio 0
	s_waitcnt lgkmcnt(0)
	s_branch .Lpipe_loop
